# P12 split-K sample tile: hand-written K loop with 6 k-steps (36 loads) in flight per wave instead of ~20 dependent round trips
# baseline (speedup 1.0000x reference)
.LBB0_1387:
	s_ashr_i32 s14, s13, 6
	s_bfe_u32 s15, s13, 0x20004
	s_and_b32 s17, s3, 0x1e0
	s_lshl_b32 s8, s14, 8
	s_lshl_b32 s10, s15, 5
	s_or_b32 s16, s10, s8
	s_bitset1_b32 s17, 14
	s_waitcnt lgkmcnt(0)
	v_mad_i64_i32 v[6:7], s[10:11], s16, v18, v[4:5]
	s_mul_i32 s8, s17, 0x1600
	s_mov_b64 s[72:73], 0x16000
	s_mov_b64 s[74:75], 0xb0000
	v_lshl_add_u64 v[10:11], v[2:3], 0, s[8:9]
	v_lshl_add_u64 v[14:15], v[6:7], 0, s[72:73]
	v_lshl_add_u64 v[12:13], v[6:7], 0, s[74:75]
	v_lshl_add_u64 v[8:9], v[10:11], 0, s[72:73]
	v_lshl_add_u64 v[96:97], v[12:13], 0, s[72:73]
	global_load_dwordx4 v[52:55], v[6:7], off
	global_load_dwordx4 v[56:59], v[10:11], off
	global_load_dwordx4 v[60:63], v[8:9], off
	global_load_dwordx4 v[64:67], v[14:15], off
	global_load_dwordx4 v[68:71], v[12:13], off
	global_load_dwordx4 v[72:75], v[96:97], off
	global_load_dwordx4 v[76:79], v[6:7], off offset:64
	global_load_dwordx4 v[80:83], v[10:11], off offset:64
	global_load_dwordx4 v[84:87], v[8:9], off offset:64
	global_load_dwordx4 v[88:91], v[14:15], off offset:64
	global_load_dwordx4 v[92:95], v[12:13], off offset:64
	global_load_dwordx4 v[144:147], v[96:97], off offset:64
	global_load_dwordx4 v[148:151], v[6:7], off offset:128
	global_load_dwordx4 v[152:155], v[10:11], off offset:128
	global_load_dwordx4 v[156:159], v[8:9], off offset:128
	global_load_dwordx4 v[160:163], v[14:15], off offset:128
	global_load_dwordx4 v[164:167], v[12:13], off offset:128
	global_load_dwordx4 v[168:171], v[96:97], off offset:128
	global_load_dwordx4 v[172:175], v[6:7], off offset:192
	global_load_dwordx4 v[176:179], v[10:11], off offset:192
	global_load_dwordx4 v[192:195], v[8:9], off offset:192
	global_load_dwordx4 v[196:199], v[14:15], off offset:192
	global_load_dwordx4 v[200:203], v[12:13], off offset:192
	global_load_dwordx4 v[204:207], v[96:97], off offset:192
	global_load_dwordx4 v[208:211], v[6:7], off offset:256
	global_load_dwordx4 v[212:215], v[10:11], off offset:256
	global_load_dwordx4 v[216:219], v[8:9], off offset:256
	global_load_dwordx4 v[220:223], v[14:15], off offset:256
	global_load_dwordx4 v[224:227], v[12:13], off offset:256
	global_load_dwordx4 v[228:231], v[96:97], off offset:256
	global_load_dwordx4 v[232:235], v[6:7], off offset:320
	global_load_dwordx4 v[236:239], v[10:11], off offset:320
	global_load_dwordx4 v[240:243], v[8:9], off offset:320
	global_load_dwordx4 v[244:247], v[14:15], off offset:320
	global_load_dwordx4 v[248:251], v[12:13], off offset:320
	global_load_dwordx4 v[138:141], v[96:97], off offset:320
	s_waitcnt vmcnt(30)
	v_mfma_f32_16x16x32_bf16 v[20:23], v[52:55], v[56:59], 0
	v_mfma_f32_16x16x32_bf16 v[36:39], v[52:55], v[60:63], 0
	v_mfma_f32_16x16x32_bf16 v[24:27], v[64:67], v[56:59], 0
	v_mfma_f32_16x16x32_bf16 v[40:43], v[64:67], v[60:63], 0
	v_mfma_f32_16x16x32_bf16 v[28:31], v[68:71], v[56:59], 0
	v_mfma_f32_16x16x32_bf16 v[44:47], v[68:71], v[60:63], 0
	v_mfma_f32_16x16x32_bf16 v[32:35], v[72:75], v[56:59], 0
	v_mfma_f32_16x16x32_bf16 v[48:51], v[72:75], v[60:63], 0
	global_load_dwordx4 v[52:55], v[6:7], off offset:384
	global_load_dwordx4 v[56:59], v[10:11], off offset:384
	global_load_dwordx4 v[60:63], v[8:9], off offset:384
	global_load_dwordx4 v[64:67], v[14:15], off offset:384
	global_load_dwordx4 v[68:71], v[12:13], off offset:384
	global_load_dwordx4 v[72:75], v[96:97], off offset:384
	s_waitcnt vmcnt(30)
	v_mfma_f32_16x16x32_bf16 v[20:23], v[76:79], v[80:83], v[20:23]
	v_mfma_f32_16x16x32_bf16 v[36:39], v[76:79], v[84:87], v[36:39]
	v_mfma_f32_16x16x32_bf16 v[24:27], v[88:91], v[80:83], v[24:27]
	v_mfma_f32_16x16x32_bf16 v[40:43], v[88:91], v[84:87], v[40:43]
	v_mfma_f32_16x16x32_bf16 v[28:31], v[92:95], v[80:83], v[28:31]
	v_mfma_f32_16x16x32_bf16 v[44:47], v[92:95], v[84:87], v[44:47]
	v_mfma_f32_16x16x32_bf16 v[32:35], v[144:147], v[80:83], v[32:35]
	v_mfma_f32_16x16x32_bf16 v[48:51], v[144:147], v[84:87], v[48:51]
	global_load_dwordx4 v[76:79], v[6:7], off offset:448
	global_load_dwordx4 v[80:83], v[10:11], off offset:448
	global_load_dwordx4 v[84:87], v[8:9], off offset:448
	global_load_dwordx4 v[88:91], v[14:15], off offset:448
	global_load_dwordx4 v[92:95], v[12:13], off offset:448
	global_load_dwordx4 v[144:147], v[96:97], off offset:448
	s_waitcnt vmcnt(30)
	v_mfma_f32_16x16x32_bf16 v[20:23], v[148:151], v[152:155], v[20:23]
	v_mfma_f32_16x16x32_bf16 v[36:39], v[148:151], v[156:159], v[36:39]
	v_mfma_f32_16x16x32_bf16 v[24:27], v[160:163], v[152:155], v[24:27]
	v_mfma_f32_16x16x32_bf16 v[40:43], v[160:163], v[156:159], v[40:43]
	v_mfma_f32_16x16x32_bf16 v[28:31], v[164:167], v[152:155], v[28:31]
	v_mfma_f32_16x16x32_bf16 v[44:47], v[164:167], v[156:159], v[44:47]
	v_mfma_f32_16x16x32_bf16 v[32:35], v[168:171], v[152:155], v[32:35]
	v_mfma_f32_16x16x32_bf16 v[48:51], v[168:171], v[156:159], v[48:51]
	global_load_dwordx4 v[148:151], v[6:7], off offset:512
	global_load_dwordx4 v[152:155], v[10:11], off offset:512
	global_load_dwordx4 v[156:159], v[8:9], off offset:512
	global_load_dwordx4 v[160:163], v[14:15], off offset:512
	global_load_dwordx4 v[164:167], v[12:13], off offset:512
	global_load_dwordx4 v[168:171], v[96:97], off offset:512
	s_waitcnt vmcnt(30)
	v_mfma_f32_16x16x32_bf16 v[20:23], v[172:175], v[176:179], v[20:23]
	v_mfma_f32_16x16x32_bf16 v[36:39], v[172:175], v[192:195], v[36:39]
	v_mfma_f32_16x16x32_bf16 v[24:27], v[196:199], v[176:179], v[24:27]
	v_mfma_f32_16x16x32_bf16 v[40:43], v[196:199], v[192:195], v[40:43]
	v_mfma_f32_16x16x32_bf16 v[28:31], v[200:203], v[176:179], v[28:31]
	v_mfma_f32_16x16x32_bf16 v[44:47], v[200:203], v[192:195], v[44:47]
	v_mfma_f32_16x16x32_bf16 v[32:35], v[204:207], v[176:179], v[32:35]
	v_mfma_f32_16x16x32_bf16 v[48:51], v[204:207], v[192:195], v[48:51]
	global_load_dwordx4 v[172:175], v[6:7], off offset:576
	global_load_dwordx4 v[176:179], v[10:11], off offset:576
	global_load_dwordx4 v[192:195], v[8:9], off offset:576
	global_load_dwordx4 v[196:199], v[14:15], off offset:576
	global_load_dwordx4 v[200:203], v[12:13], off offset:576
	global_load_dwordx4 v[204:207], v[96:97], off offset:576
	s_waitcnt vmcnt(30)
	v_mfma_f32_16x16x32_bf16 v[20:23], v[208:211], v[212:215], v[20:23]
	v_mfma_f32_16x16x32_bf16 v[36:39], v[208:211], v[216:219], v[36:39]
	v_mfma_f32_16x16x32_bf16 v[24:27], v[220:223], v[212:215], v[24:27]
	v_mfma_f32_16x16x32_bf16 v[40:43], v[220:223], v[216:219], v[40:43]
	v_mfma_f32_16x16x32_bf16 v[28:31], v[224:227], v[212:215], v[28:31]
	v_mfma_f32_16x16x32_bf16 v[44:47], v[224:227], v[216:219], v[44:47]
	v_mfma_f32_16x16x32_bf16 v[32:35], v[228:231], v[212:215], v[32:35]
	v_mfma_f32_16x16x32_bf16 v[48:51], v[228:231], v[216:219], v[48:51]
	global_load_dwordx4 v[208:211], v[6:7], off offset:640
	global_load_dwordx4 v[212:215], v[10:11], off offset:640
	global_load_dwordx4 v[216:219], v[8:9], off offset:640
	global_load_dwordx4 v[220:223], v[14:15], off offset:640
	global_load_dwordx4 v[224:227], v[12:13], off offset:640
	global_load_dwordx4 v[228:231], v[96:97], off offset:640
	s_waitcnt vmcnt(30)
	v_mfma_f32_16x16x32_bf16 v[20:23], v[232:235], v[236:239], v[20:23]
	v_mfma_f32_16x16x32_bf16 v[36:39], v[232:235], v[240:243], v[36:39]
	v_mfma_f32_16x16x32_bf16 v[24:27], v[244:247], v[236:239], v[24:27]
	v_mfma_f32_16x16x32_bf16 v[40:43], v[244:247], v[240:243], v[40:43]
	v_mfma_f32_16x16x32_bf16 v[28:31], v[248:251], v[236:239], v[28:31]
	v_mfma_f32_16x16x32_bf16 v[44:47], v[248:251], v[240:243], v[44:47]
	v_mfma_f32_16x16x32_bf16 v[32:35], v[138:141], v[236:239], v[32:35]
	v_mfma_f32_16x16x32_bf16 v[48:51], v[138:141], v[240:243], v[48:51]
	s_waitcnt vmcnt(24)
	v_mfma_f32_16x16x32_bf16 v[20:23], v[52:55], v[56:59], v[20:23]
	v_mfma_f32_16x16x32_bf16 v[36:39], v[52:55], v[60:63], v[36:39]
	v_mfma_f32_16x16x32_bf16 v[24:27], v[64:67], v[56:59], v[24:27]
	v_mfma_f32_16x16x32_bf16 v[40:43], v[64:67], v[60:63], v[40:43]
	v_mfma_f32_16x16x32_bf16 v[28:31], v[68:71], v[56:59], v[28:31]
	v_mfma_f32_16x16x32_bf16 v[44:47], v[68:71], v[60:63], v[44:47]
	v_mfma_f32_16x16x32_bf16 v[32:35], v[72:75], v[56:59], v[32:35]
	v_mfma_f32_16x16x32_bf16 v[48:51], v[72:75], v[60:63], v[48:51]
	s_waitcnt vmcnt(18)
	v_mfma_f32_16x16x32_bf16 v[20:23], v[76:79], v[80:83], v[20:23]
	v_mfma_f32_16x16x32_bf16 v[36:39], v[76:79], v[84:87], v[36:39]
	v_mfma_f32_16x16x32_bf16 v[24:27], v[88:91], v[80:83], v[24:27]
	v_mfma_f32_16x16x32_bf16 v[40:43], v[88:91], v[84:87], v[40:43]
	v_mfma_f32_16x16x32_bf16 v[28:31], v[92:95], v[80:83], v[28:31]
	v_mfma_f32_16x16x32_bf16 v[44:47], v[92:95], v[84:87], v[44:47]
	v_mfma_f32_16x16x32_bf16 v[32:35], v[144:147], v[80:83], v[32:35]
	v_mfma_f32_16x16x32_bf16 v[48:51], v[144:147], v[84:87], v[48:51]
	s_waitcnt vmcnt(12)
	v_mfma_f32_16x16x32_bf16 v[20:23], v[148:151], v[152:155], v[20:23]
	v_mfma_f32_16x16x32_bf16 v[36:39], v[148:151], v[156:159], v[36:39]
	v_mfma_f32_16x16x32_bf16 v[24:27], v[160:163], v[152:155], v[24:27]
	v_mfma_f32_16x16x32_bf16 v[40:43], v[160:163], v[156:159], v[40:43]
	v_mfma_f32_16x16x32_bf16 v[28:31], v[164:167], v[152:155], v[28:31]
	v_mfma_f32_16x16x32_bf16 v[44:47], v[164:167], v[156:159], v[44:47]
	v_mfma_f32_16x16x32_bf16 v[32:35], v[168:171], v[152:155], v[32:35]
	v_mfma_f32_16x16x32_bf16 v[48:51], v[168:171], v[156:159], v[48:51]
	s_waitcnt vmcnt(6)
	v_mfma_f32_16x16x32_bf16 v[20:23], v[172:175], v[176:179], v[20:23]
	v_mfma_f32_16x16x32_bf16 v[36:39], v[172:175], v[192:195], v[36:39]
	v_mfma_f32_16x16x32_bf16 v[24:27], v[196:199], v[176:179], v[24:27]
	v_mfma_f32_16x16x32_bf16 v[40:43], v[196:199], v[192:195], v[40:43]
	v_mfma_f32_16x16x32_bf16 v[28:31], v[200:203], v[176:179], v[28:31]
	v_mfma_f32_16x16x32_bf16 v[44:47], v[200:203], v[192:195], v[44:47]
	v_mfma_f32_16x16x32_bf16 v[32:35], v[204:207], v[176:179], v[32:35]
	v_mfma_f32_16x16x32_bf16 v[48:51], v[204:207], v[192:195], v[48:51]
	s_waitcnt vmcnt(0)
	v_mfma_f32_16x16x32_bf16 v[20:23], v[208:211], v[212:215], v[20:23]
	v_mfma_f32_16x16x32_bf16 v[36:39], v[208:211], v[216:219], v[36:39]
	v_mfma_f32_16x16x32_bf16 v[24:27], v[220:223], v[212:215], v[24:27]
	v_mfma_f32_16x16x32_bf16 v[40:43], v[220:223], v[216:219], v[40:43]
	v_mfma_f32_16x16x32_bf16 v[28:31], v[224:227], v[212:215], v[28:31]
	v_mfma_f32_16x16x32_bf16 v[44:47], v[224:227], v[216:219], v[44:47]
	v_mfma_f32_16x16x32_bf16 v[32:35], v[228:231], v[212:215], v[32:35]
	v_mfma_f32_16x16x32_bf16 v[48:51], v[228:231], v[216:219], v[48:51]
	s_nop 7
	s_nop 7
	s_barrier
	ds_write2st64_b32 v19, v20, v21 offset1:1
	ds_write2st64_b32 v19, v22, v23 offset0:2 offset1:3
	ds_write2st64_b32 v19, v36, v37 offset0:16 offset1:17
	ds_write2st64_b32 v19, v38, v39 offset0:18 offset1:19
	ds_write2st64_b32 v19, v24, v25 offset0:4 offset1:5
	ds_write2st64_b32 v19, v26, v27 offset0:6 offset1:7
	ds_write2st64_b32 v19, v40, v41 offset0:20 offset1:21
	ds_write2st64_b32 v19, v42, v43 offset0:22 offset1:23
	ds_write2st64_b32 v19, v28, v29 offset0:8 offset1:9
	ds_write2st64_b32 v19, v30, v31 offset0:10 offset1:11
	ds_write2st64_b32 v19, v44, v45 offset0:24 offset1:25
	ds_write2st64_b32 v19, v46, v47 offset0:26 offset1:27
	ds_write2st64_b32 v19, v32, v33 offset0:12 offset1:13
	ds_write2st64_b32 v19, v34, v35 offset0:14 offset1:15
	ds_write2st64_b32 v19, v48, v49 offset0:28 offset1:29
	ds_write2st64_b32 v19, v50, v51 offset0:30 offset1:31
	s_waitcnt lgkmcnt(0)
	s_barrier
	s_and_saveexec_b64 s[10:11], s[0:1]
	s_cbranch_execz .LBB0_1386
	ds_read2st64_b32 v[6:7], v16 offset0:128 offset1:129
	ds_read2st64_b32 v[8:9], v16 offset0:136 offset1:137
	ds_read2st64_b32 v[10:11], v16 offset0:138 offset1:139
	ds_read2st64_b32 v[12:13], v16 offset0:130 offset1:131
	s_waitcnt lgkmcnt(3)
	v_add_f32_e32 v0, 0, v6
	s_waitcnt lgkmcnt(2)
	v_add_f32_e32 v14, 0, v8
	v_add_f32_e32 v15, 0, v7
	v_add_f32_e32 v20, 0, v9
	ds_read2st64_b32 v[6:7], v16 offset0:160 offset1:161
	ds_read2st64_b32 v[8:9], v16 offset0:168 offset1:169
	s_waitcnt lgkmcnt(2)
	v_add_f32_e32 v21, 0, v12
	v_add_f32_e32 v22, 0, v10
	v_add_f32_e32 v23, 0, v13
	v_add_f32_e32 v24, 0, v11
	ds_read2st64_b32 v[10:11], v16 offset0:170 offset1:171
	ds_read2st64_b32 v[12:13], v16 offset0:162 offset1:163
	s_waitcnt lgkmcnt(3)
	v_add_f32_e32 v0, v0, v6
	s_waitcnt lgkmcnt(2)
	v_add_f32_e32 v14, v14, v8
	v_add_f32_e32 v15, v15, v7
	v_add_f32_e32 v20, v20, v9
	ds_read2st64_b32 v[6:7], v16 offset0:192 offset1:193
	ds_read2st64_b32 v[8:9], v16 offset0:200 offset1:201
	s_waitcnt lgkmcnt(2)
	v_add_f32_e32 v21, v21, v12
	v_add_f32_e32 v22, v22, v10
	v_add_f32_e32 v23, v23, v13
	v_add_f32_e32 v24, v24, v11
	ds_read2st64_b32 v[10:11], v16 offset0:202 offset1:203
	ds_read2st64_b32 v[12:13], v16 offset0:194 offset1:195
	s_waitcnt lgkmcnt(3)
	v_add_f32_e32 v0, v0, v6
	s_waitcnt lgkmcnt(2)
	v_add_f32_e32 v14, v14, v8
	v_add_f32_e32 v15, v15, v7
	v_add_f32_e32 v20, v20, v9
	ds_read2st64_b32 v[6:7], v16 offset0:224 offset1:225
	ds_read2st64_b32 v[8:9], v16 offset0:232 offset1:233
	s_waitcnt lgkmcnt(2)
	v_add_f32_e32 v21, v21, v12
	v_add_f32_e32 v22, v22, v10
	v_add_f32_e32 v23, v23, v13
	v_add_f32_e32 v24, v24, v11
	ds_read2st64_b32 v[10:11], v16 offset0:234 offset1:235
	ds_read2st64_b32 v[12:13], v16 offset0:226 offset1:227
	s_waitcnt lgkmcnt(3)
	v_add_f32_e32 v0, v0, v6
	s_waitcnt lgkmcnt(2)
	v_add_f32_e32 v14, v14, v8
	v_add_f32_e32 v15, v15, v7
	v_add_f32_e32 v20, v20, v9
	ds_read2st64_b32 v[6:7], v184 offset0:128 offset1:129
	ds_read2st64_b32 v[8:9], v184 offset0:136 offset1:137
	s_waitcnt lgkmcnt(2)
	v_add_f32_e32 v21, v21, v12
	v_add_f32_e32 v22, v22, v10
	v_add_f32_e32 v23, v23, v13
	v_add_f32_e32 v24, v24, v11
	ds_read2st64_b32 v[10:11], v184 offset0:138 offset1:139
	ds_read2st64_b32 v[12:13], v184 offset0:130 offset1:131
	s_waitcnt lgkmcnt(3)
	v_add_f32_e32 v0, v0, v6
	s_waitcnt lgkmcnt(2)
	v_add_f32_e32 v14, v14, v8
	v_add_f32_e32 v15, v15, v7
	v_add_f32_e32 v20, v20, v9
	ds_read2st64_b32 v[6:7], v184 offset0:160 offset1:161
	ds_read2st64_b32 v[8:9], v184 offset0:168 offset1:169
	s_waitcnt lgkmcnt(2)
	v_add_f32_e32 v21, v21, v12
	v_add_f32_e32 v22, v22, v10
	v_add_f32_e32 v23, v23, v13
	v_add_f32_e32 v24, v24, v11
	ds_read2st64_b32 v[10:11], v184 offset0:170 offset1:171
	ds_read2st64_b32 v[12:13], v184 offset0:162 offset1:163
	s_waitcnt lgkmcnt(3)
	v_add_f32_e32 v0, v0, v6
	s_waitcnt lgkmcnt(2)
	v_add_f32_e32 v14, v14, v8
	v_add_f32_e32 v15, v15, v7
	v_add_f32_e32 v20, v20, v9
	ds_read2st64_b32 v[6:7], v184 offset0:192 offset1:193
	ds_read2st64_b32 v[8:9], v184 offset0:200 offset1:201
	s_waitcnt lgkmcnt(2)
	v_add_f32_e32 v21, v21, v12
	v_add_f32_e32 v22, v22, v10
	v_add_f32_e32 v23, v23, v13
	v_add_f32_e32 v24, v24, v11
	ds_read2st64_b32 v[10:11], v184 offset0:202 offset1:203
	ds_read2st64_b32 v[12:13], v184 offset0:194 offset1:195
	s_waitcnt lgkmcnt(3)
	v_add_f32_e32 v0, v0, v6
	s_waitcnt lgkmcnt(2)
	v_add_f32_e32 v14, v14, v8
	v_add_f32_e32 v15, v15, v7
	v_add_f32_e32 v20, v20, v9
	ds_read2st64_b32 v[6:7], v184 offset0:224 offset1:225
	ds_read2st64_b32 v[8:9], v184 offset0:232 offset1:233
	s_waitcnt lgkmcnt(2)
	v_add_f32_e32 v21, v21, v12
	v_add_f32_e32 v22, v22, v10
	v_add_f32_e32 v23, v23, v13
	v_add_f32_e32 v24, v24, v11
	ds_read2st64_b32 v[10:11], v184 offset0:234 offset1:235
	ds_read2st64_b32 v[12:13], v184 offset0:226 offset1:227
	s_waitcnt lgkmcnt(3)
	v_add_f32_e32 v7, v15, v7
	s_waitcnt lgkmcnt(2)
	v_add_f32_e32 v15, v20, v9
	v_add_f32_e32 v25, v0, v6
	v_add_f32_e32 v14, v14, v8
	v_mul_f32_e32 v0, v7, v7
	v_mul_f32_e32 v6, v15, v15
	s_waitcnt lgkmcnt(0)
	v_add_f32_e32 v12, v21, v12
	v_add_f32_e32 v20, v22, v10
	v_fmac_f32_e32 v0, v25, v25
	v_fmac_f32_e32 v6, v14, v14
	v_add_f32_e32 v13, v23, v13
	v_add_f32_e32 v21, v24, v11
	v_fmac_f32_e32 v0, v12, v12
	v_fmac_f32_e32 v6, v20, v20
	v_fmac_f32_e32 v0, v13, v13
	v_fmac_f32_e32 v6, v21, v21
	v_add_f32_e32 v9, v0, v6
	v_and_b32_e32 v6, 64, v137
	v_xor_b32_e32 v0, 1, v137
	v_add_u32_e32 v22, 64, v6
	v_cmp_lt_i32_e32 vcc, v0, v22
	v_or_b32_e32 v6, s17, v182
	v_or_b32_e32 v8, s16, v17
	v_cndmask_b32_e32 v0, v137, v0, vcc
	v_lshlrev_b32_e32 v0, 2, v0
	ds_bpermute_b32 v23, v0, v9
	v_lshlrev_b32_e32 v0, 11, v6
	v_lshl_add_u64 v[10:11], s[58:59], 0, v[0:1]
	s_waitcnt lgkmcnt(0)
	v_add_f32_e32 v0, v9, v23
	v_xor_b32_e32 v9, 2, v137
	v_cmp_lt_i32_e32 vcc, v9, v22
	s_nop 1
	v_cndmask_b32_e32 v9, v137, v9, vcc
	v_lshlrev_b32_e32 v9, 2, v9
	ds_bpermute_b32 v23, v9, v0
	v_ashrrev_i32_e32 v9, 31, v8
	v_lshl_add_u64 v[8:9], v[8:9], 1, v[10:11]
	v_cvt_pk_bf16_f32 v10, v25, v7
	v_xor_b32_e32 v7, 4, v137
	v_cmp_lt_i32_e32 vcc, v7, v22
	s_waitcnt lgkmcnt(0)
	v_add_f32_e32 v0, v0, v23
	v_cvt_pk_bf16_f32 v11, v12, v13
	global_store_dwordx2 v[8:9], v[10:11], off
	v_cndmask_b32_e32 v7, v137, v7, vcc
	v_lshlrev_b32_e32 v7, 2, v7
	ds_bpermute_b32 v7, v7, v0
	v_cvt_pk_bf16_f32 v10, v14, v15
	v_cvt_pk_bf16_f32 v11, v20, v21
	global_store_dwordx2 v[8:9], v[10:11], off offset:256
	s_and_b64 exec, exec, s[4:5]
	s_cbranch_execz .LBB0_1386
	s_lshl_b32 s8, s14, 2
	s_or_b32 s8, s8, s15
	s_mul_hi_i32 s15, s8, 0x10800
	s_mul_i32 s8, s8, 0x10800
	s_add_u32 s14, s44, s8
	s_waitcnt lgkmcnt(0)
	v_add_f32_e32 v0, v0, v7
	s_addc_u32 s15, s45, s15
	v_lshlrev_b32_e32 v6, 2, v6
	global_store_dword v6, v0, s[14:15]
	s_branch .LBB0_1386
